# DSA attend QK loop tail: vmcnt(15..0) ladder collapsed to one vmcnt(0) before the operand copies
# baseline (speedup 1.0000x reference)
.LBB0_268:
	s_add_i32 s43, s43, 4
	v_add_u32_e32 v206, 64, v206
	s_cmp_ge_u32 s76, s42
	v_add_u32_e32 v205, 0x800, v205
	s_cbranch_scc1 .LBB0_270
	s_waitcnt vmcnt(0)
	v_mov_b64_e32 v[144:145], v[128:129]
	v_mov_b64_e32 v[140:141], v[124:125]
	v_mov_b64_e32 v[136:137], v[120:121]
	v_mov_b64_e32 v[132:133], v[116:117]
	v_mov_b64_e32 v[96:97], v[64:65]
	v_mov_b64_e32 v[92:93], v[60:61]
	v_mov_b64_e32 v[72:73], v[56:57]
	v_mov_b64_e32 v[68:69], v[52:53]
	v_mov_b64_e32 v[46:47], v[86:87]
	v_mov_b64_e32 v[42:43], v[82:83]
	v_mov_b64_e32 v[38:39], v[78:79]
	v_mov_b64_e32 v[34:35], v[74:75]
	v_mov_b64_e32 v[30:31], v[110:111]
	v_mov_b64_e32 v[26:27], v[106:107]
	v_mov_b64_e32 v[22:23], v[102:103]
	v_mov_b64_e32 v[18:19], v[98:99]
	v_mov_b64_e32 v[142:143], v[126:127]
	v_mov_b64_e32 v[138:139], v[122:123]
	v_mov_b64_e32 v[134:135], v[118:119]
	v_mov_b64_e32 v[130:131], v[114:115]
	v_mov_b64_e32 v[94:95], v[62:63]
	v_mov_b64_e32 v[90:91], v[58:59]
	v_mov_b64_e32 v[70:71], v[54:55]
	v_mov_b64_e32 v[66:67], v[50:51]
	v_mov_b64_e32 v[48:49], v[88:89]
	v_mov_b64_e32 v[44:45], v[84:85]
	v_mov_b64_e32 v[40:41], v[80:81]
	v_mov_b64_e32 v[36:37], v[76:77]
	v_mov_b64_e32 v[32:33], v[112:113]
	v_mov_b64_e32 v[28:29], v[108:109]
	v_mov_b64_e32 v[24:25], v[104:105]
	v_mov_b64_e32 v[20:21], v[100:101]
	s_add_i32 s76, s43, 2
	s_cmp_ge_u32 s76, s42
	s_cbranch_scc0 .LBB0_253
	s_branch .LBB0_254
